# nt (streaming) policy also on the w_mod GEMV loads, layer-0 norm x loads and final output stores
# speedup vs baseline: 1.0116x; 1.0096x over previous
.LBB0_52:
	global_load_dwordx4 v[22:25], v[18:19], off offset:-8 nt
	ds_read2st64_b32 v[26:27], v12 offset1:64
	ds_read_b32 v28, v12 offset:32768
	s_mov_b64 s[34:35], 0xfc000
	v_add_co_u32_e32 v21, vcc, 1, v21
	s_waitcnt lgkmcnt(1)
	v_mov_b32_e32 v30, v27
	v_add_u32_e32 v34, 21, v34
	v_add_u32_e32 v12, 0x54, v12
	v_lshl_add_u64 v[18:19], v[18:19], 0, s[34:35]
	s_or_b64 s[4:5], vcc, s[4:5]
	s_waitcnt vmcnt(0)
	v_pk_fma_f32 v[0:1], v[22:23], v[26:27], v[0:1] op_sel_hi:[1,0,1]
	v_pk_fma_f32 v[2:3], v[24:25], v[26:27], v[2:3] op_sel_hi:[1,0,1]
	v_pk_fma_f32 v[8:9], v[22:23], v[30:31], v[8:9] op_sel_hi:[1,0,1]
	v_pk_fma_f32 v[10:11], v[24:25], v[30:31], v[10:11] op_sel_hi:[1,0,1]
	s_waitcnt lgkmcnt(0)
	v_pk_fma_f32 v[4:5], v[22:23], v[28:29], v[4:5] op_sel_hi:[1,0,1]
	v_pk_fma_f32 v[6:7], v[24:25], v[28:29], v[6:7] op_sel_hi:[1,0,1]
	s_andn2_b64 exec, exec, s[4:5]
	s_cbranch_execnz .LBB0_52
	s_or_b64 exec, exec, s[4:5]

.LBB0_56:
	v_lshl_add_u64 v[50:51], v[20:21], 0, v[18:19]
	v_lshl_add_u64 v[54:55], v[26:27], 0, v[18:19]
	v_lshl_add_u64 v[58:59], v[30:31], 0, v[18:19]
	v_lshl_add_u64 v[62:63], v[34:35], 0, v[18:19]
	v_lshl_add_u64 v[66:67], v[32:33], 0, v[18:19]
	v_lshl_add_u64 v[70:71], v[28:29], 0, v[18:19]
	v_lshl_add_u64 v[74:75], v[24:25], 0, v[18:19]
	v_lshl_add_u64 v[78:79], v[22:23], 0, v[18:19]
	ds_read2_b32 v[82:83], v17 offset1:21
	ds_read2_b32 v[84:85], v17 offset0:42 offset1:63
	ds_read2_b32 v[86:87], v17 offset0:84 offset1:105
	ds_read2_b32 v[88:89], v17 offset0:126 offset1:147
	global_load_dwordx4 v[50:53], v[50:51], off nt
	s_nop 0
	global_load_dwordx4 v[54:57], v[54:55], off nt
	s_nop 0
	global_load_dwordx4 v[58:61], v[58:59], off nt
	s_nop 0
	global_load_dwordx4 v[62:65], v[62:63], off offset:-8 nt
	s_nop 0
	global_load_dwordx4 v[66:69], v[66:67], off offset:-8 nt
	s_nop 0
	global_load_dwordx4 v[70:73], v[70:71], off offset:-8 nt
	s_nop 0
	global_load_dwordx4 v[74:77], v[74:75], off offset:-8 nt
	s_nop 0
	global_load_dwordx4 v[78:81], v[78:79], off offset:-8 nt
	v_add_u32_e32 v49, 0x4000, v17
	v_add_u32_e32 v104, 0x8000, v17
	ds_read2_b32 v[90:91], v49 offset1:21
	ds_read2_b32 v[92:93], v104 offset1:21
	ds_read2_b32 v[94:95], v49 offset0:42 offset1:63
	ds_read2_b32 v[96:97], v104 offset0:42 offset1:63
	ds_read2_b32 v[98:99], v49 offset0:84 offset1:105
	ds_read2_b32 v[100:101], v104 offset0:84 offset1:105
	ds_read2_b32 v[102:103], v49 offset0:126 offset1:147
	ds_read2_b32 v[104:105], v104 offset0:126 offset1:147
	s_waitcnt lgkmcnt(11)
	v_mov_b32_e32 v106, v83
	s_waitcnt lgkmcnt(7)
	v_mov_b32_e32 v114, v91
	s_waitcnt lgkmcnt(6)
	v_mov_b32_e32 v116, v93
	v_mov_b32_e32 v108, v85
	s_waitcnt lgkmcnt(5)
	v_mov_b32_e32 v118, v95
	s_waitcnt lgkmcnt(4)
	v_mov_b32_e32 v120, v97
	v_mov_b32_e32 v110, v87
	s_waitcnt lgkmcnt(3)
	v_mov_b32_e32 v122, v99
	s_waitcnt lgkmcnt(2)
	v_mov_b32_e32 v124, v101
	v_add_u32_e32 v12, 0xa8, v12
	s_movk_i32 s7, 0xf57
	v_cmp_lt_i32_e32 vcc, s7, v12
	v_mov_b32_e32 v112, v89
	s_waitcnt lgkmcnt(1)
	v_mov_b32_e32 v126, v103
	s_waitcnt lgkmcnt(0)
	v_mov_b32_e32 v128, v105
	v_lshl_add_u64 v[20:21], v[20:21], 0, s[14:15]
	v_lshl_add_u64 v[22:23], v[22:23], 0, s[14:15]
	v_add_u32_e32 v17, 0x2a0, v17
	v_lshl_add_u64 v[24:25], v[24:25], 0, s[14:15]
	v_lshl_add_u64 v[26:27], v[26:27], 0, s[14:15]
	v_lshl_add_u64 v[28:29], v[28:29], 0, s[14:15]
	v_lshl_add_u64 v[30:31], v[30:31], 0, s[14:15]
	v_lshl_add_u64 v[32:33], v[32:33], 0, s[14:15]
	v_lshl_add_u64 v[34:35], v[34:35], 0, s[14:15]
	s_or_b64 s[4:5], vcc, s[4:5]
	s_waitcnt vmcnt(7)
	v_pk_fma_f32 v[0:1], v[50:51], v[82:83], v[0:1] op_sel_hi:[1,0,1]
	v_pk_fma_f32 v[2:3], v[52:53], v[82:83], v[2:3] op_sel_hi:[1,0,1]
	v_pk_fma_f32 v[8:9], v[50:51], v[90:91], v[8:9] op_sel_hi:[1,0,1]
	v_pk_fma_f32 v[10:11], v[52:53], v[90:91], v[10:11] op_sel_hi:[1,0,1]
	v_pk_fma_f32 v[4:5], v[50:51], v[92:93], v[4:5] op_sel_hi:[1,0,1]
	v_pk_fma_f32 v[6:7], v[52:53], v[92:93], v[6:7] op_sel_hi:[1,0,1]
	s_waitcnt vmcnt(6)
	v_pk_fma_f32 v[0:1], v[54:55], v[106:107], v[0:1] op_sel_hi:[1,0,1]
	v_pk_fma_f32 v[2:3], v[56:57], v[106:107], v[2:3] op_sel_hi:[1,0,1]
	v_pk_fma_f32 v[8:9], v[54:55], v[114:115], v[8:9] op_sel_hi:[1,0,1]
	v_pk_fma_f32 v[10:11], v[56:57], v[114:115], v[10:11] op_sel_hi:[1,0,1]
	v_pk_fma_f32 v[4:5], v[54:55], v[116:117], v[4:5] op_sel_hi:[1,0,1]
	v_pk_fma_f32 v[6:7], v[56:57], v[116:117], v[6:7] op_sel_hi:[1,0,1]
	s_waitcnt vmcnt(5)
	v_pk_fma_f32 v[0:1], v[58:59], v[84:85], v[0:1] op_sel_hi:[1,0,1]
	v_pk_fma_f32 v[2:3], v[60:61], v[84:85], v[2:3] op_sel_hi:[1,0,1]
	v_pk_fma_f32 v[8:9], v[58:59], v[94:95], v[8:9] op_sel_hi:[1,0,1]
	v_pk_fma_f32 v[10:11], v[60:61], v[94:95], v[10:11] op_sel_hi:[1,0,1]
	v_pk_fma_f32 v[4:5], v[58:59], v[96:97], v[4:5] op_sel_hi:[1,0,1]
	v_pk_fma_f32 v[6:7], v[60:61], v[96:97], v[6:7] op_sel_hi:[1,0,1]
	s_waitcnt vmcnt(4)
	v_pk_fma_f32 v[0:1], v[62:63], v[108:109], v[0:1] op_sel_hi:[1,0,1]
	v_pk_fma_f32 v[2:3], v[64:65], v[108:109], v[2:3] op_sel_hi:[1,0,1]
	v_pk_fma_f32 v[8:9], v[62:63], v[118:119], v[8:9] op_sel_hi:[1,0,1]
	v_pk_fma_f32 v[10:11], v[64:65], v[118:119], v[10:11] op_sel_hi:[1,0,1]
	v_pk_fma_f32 v[4:5], v[62:63], v[120:121], v[4:5] op_sel_hi:[1,0,1]
	v_pk_fma_f32 v[6:7], v[64:65], v[120:121], v[6:7] op_sel_hi:[1,0,1]
	s_waitcnt vmcnt(3)
	v_pk_fma_f32 v[0:1], v[66:67], v[86:87], v[0:1] op_sel_hi:[1,0,1]
	v_pk_fma_f32 v[2:3], v[68:69], v[86:87], v[2:3] op_sel_hi:[1,0,1]
	v_pk_fma_f32 v[8:9], v[66:67], v[98:99], v[8:9] op_sel_hi:[1,0,1]
	v_pk_fma_f32 v[10:11], v[68:69], v[98:99], v[10:11] op_sel_hi:[1,0,1]
	v_pk_fma_f32 v[4:5], v[66:67], v[100:101], v[4:5] op_sel_hi:[1,0,1]
	v_pk_fma_f32 v[6:7], v[68:69], v[100:101], v[6:7] op_sel_hi:[1,0,1]
	s_waitcnt vmcnt(2)
	v_pk_fma_f32 v[0:1], v[70:71], v[110:111], v[0:1] op_sel_hi:[1,0,1]
	v_pk_fma_f32 v[2:3], v[72:73], v[110:111], v[2:3] op_sel_hi:[1,0,1]
	v_pk_fma_f32 v[8:9], v[70:71], v[122:123], v[8:9] op_sel_hi:[1,0,1]
	v_pk_fma_f32 v[10:11], v[72:73], v[122:123], v[10:11] op_sel_hi:[1,0,1]
	v_pk_fma_f32 v[4:5], v[70:71], v[124:125], v[4:5] op_sel_hi:[1,0,1]
	v_pk_fma_f32 v[6:7], v[72:73], v[124:125], v[6:7] op_sel_hi:[1,0,1]
	s_waitcnt vmcnt(1)
	v_pk_fma_f32 v[0:1], v[74:75], v[88:89], v[0:1] op_sel_hi:[1,0,1]
	v_pk_fma_f32 v[2:3], v[76:77], v[88:89], v[2:3] op_sel_hi:[1,0,1]
	v_pk_fma_f32 v[8:9], v[74:75], v[102:103], v[8:9] op_sel_hi:[1,0,1]
	v_pk_fma_f32 v[10:11], v[76:77], v[102:103], v[10:11] op_sel_hi:[1,0,1]
	v_pk_fma_f32 v[4:5], v[74:75], v[104:105], v[4:5] op_sel_hi:[1,0,1]
	v_pk_fma_f32 v[6:7], v[76:77], v[104:105], v[6:7] op_sel_hi:[1,0,1]
	s_waitcnt vmcnt(0)
	v_pk_fma_f32 v[0:1], v[78:79], v[112:113], v[0:1] op_sel_hi:[1,0,1]
	v_pk_fma_f32 v[2:3], v[80:81], v[112:113], v[2:3] op_sel_hi:[1,0,1]
	v_pk_fma_f32 v[8:9], v[78:79], v[126:127], v[8:9] op_sel_hi:[1,0,1]
	v_pk_fma_f32 v[10:11], v[80:81], v[126:127], v[10:11] op_sel_hi:[1,0,1]
	v_pk_fma_f32 v[4:5], v[78:79], v[128:129], v[4:5] op_sel_hi:[1,0,1]
	v_pk_fma_f32 v[6:7], v[80:81], v[128:129], v[6:7] op_sel_hi:[1,0,1]
	s_andn2_b64 exec, exec, s[4:5]
	s_cbranch_execnz .LBB0_56
	s_or_b64 exec, exec, s[4:5]

.LBB0_163:
	s_or_b64 exec, exec, s[0:1]
	v_readlane_b32 s52, v254, 12
	v_readlane_b32 s60, v254, 20
	v_readlane_b32 s61, v254, 21
	v_readlane_b32 s62, v254, 22
	v_readlane_b32 s63, v254, 23
	v_readlane_b32 s64, v254, 24
	v_readlane_b32 s65, v254, 25
	v_readlane_b32 s66, v254, 26
	v_readlane_b32 s67, v254, 27
	v_and_b32_e32 v0, 63, v2
	v_readlane_b32 s60, v254, 28
	v_ashrrev_i32_e32 v1, 4, v2
	v_lshlrev_b32_e32 v2, 2, v0
	v_readlane_b32 s53, v254, 13
	v_readlane_b32 s54, v254, 14
	v_readlane_b32 s55, v254, 15
	v_readlane_b32 s61, v254, 29
	v_and_b32_e32 v1, -4, v1
	v_or_b32_e32 v4, 0x900, v2
	v_or_b32_e32 v6, 0xb00, v2
	v_or_b32_e32 v8, 0xd00, v2
	v_or_b32_e32 v10, 0xf00, v2
	v_or_b32_e32 v12, 0x800, v2
	v_or_b32_e32 v14, 0xa00, v2
	v_or_b32_e32 v16, 0xc00, v2
	v_or_b32_e32 v18, 0xe00, v2
	v_readlane_b32 s62, v254, 30
	v_readlane_b32 s63, v254, 31
	s_mov_b64 s[52:53], s[60:61]
	v_lshl_add_u32 v117, v0, 4, 0
	v_add_u32_e32 v118, s10, v1
	s_mov_b32 s6, 0
	v_lshlrev_b32_e32 v72, 4, v0
	v_lshlrev_b32_e32 v74, 1, v2
	v_lshlrev_b32_e32 v76, 1, v12
	v_mov_b32_e32 v77, v73
	v_lshlrev_b32_e32 v78, 1, v4
	v_mov_b32_e32 v79, v73
	v_lshlrev_b32_e32 v80, 1, v14
	v_mov_b32_e32 v81, v73
	v_lshlrev_b32_e32 v82, 1, v6
	v_mov_b32_e32 v83, v73
	v_lshlrev_b32_e32 v84, 1, v16
	v_mov_b32_e32 v85, v73
	v_lshlrev_b32_e32 v86, 1, v8
	v_mov_b32_e32 v87, v73
	v_lshlrev_b32_e32 v88, 1, v18
	v_mov_b32_e32 v89, v73
	v_lshlrev_b32_e32 v90, 1, v10
	v_mov_b32_e32 v91, v73
	v_mov_b32_e32 v75, v73
	v_readlane_b32 s56, v254, 16
	v_readlane_b32 s57, v254, 17
	s_mov_b64 s[54:55], s[62:63]
	s_waitcnt lgkmcnt(0)
	s_barrier
	v_readlane_b32 s58, v254, 18
	v_readlane_b32 s59, v254, 19
	v_readlane_b32 s64, v254, 32
	v_readlane_b32 s65, v254, 33
	v_readlane_b32 s66, v254, 34
	v_readlane_b32 s67, v254, 35
	v_readlane_b32 s68, v254, 36
	v_readlane_b32 s69, v254, 37
	v_readlane_b32 s70, v254, 38
	v_readlane_b32 s71, v254, 39
	v_readlane_b32 s72, v254, 40
	v_readlane_b32 s73, v254, 41
	v_readlane_b32 s74, v254, 42
	v_readlane_b32 s75, v254, 43
	s_cmpk_lt_i32 s10, 0x1000
	s_cselect_b32 s8, s52, s54
	s_cselect_b32 s9, s53, s55
	s_cselect_b32 s7, 0, 0x1000
	s_mov_b64 s[32:33], 0x1000
	s_mov_b64 s[76:77], 0x2000
	s_mov_b64 s[78:79], 0x3000
	s_mov_b64 s[34:35], 0x4000
	v_subrev_u32_e32 v250, s7, v118
	v_mov_b32_e32 v251, 0
	v_lshlrev_b64 v[250:251], 14, v[250:251]
	v_lshl_add_u64 v[250:251], v[250:251], 0, s[8:9]
	v_lshl_add_u64 v[250:251], v[250:251], 0, v[72:73]
	global_load_dwordx4 v[186:189], v[250:251], off nt
	global_load_dwordx4 v[190:193], v[250:251], off offset:1024 nt
	global_load_dwordx4 v[194:197], v[250:251], off offset:2048 nt
	global_load_dwordx4 v[198:201], v[250:251], off offset:3072 nt
	v_lshl_add_u64 v[136:137], v[250:251], 0, s[78:79]
	global_load_dwordx4 v[202:205], v[136:137], off nt
	global_load_dwordx4 v[206:209], v[136:137], off offset:1024 nt
	global_load_dwordx4 v[210:213], v[136:137], off offset:2048 nt
	global_load_dwordx4 v[214:217], v[136:137], off offset:3072 nt
	v_lshl_add_u64 v[136:137], v[250:251], 0, s[32:33]
	global_load_dwordx4 v[218:221], v[136:137], off nt
	global_load_dwordx4 v[222:225], v[136:137], off offset:1024 nt
	global_load_dwordx4 v[226:229], v[136:137], off offset:2048 nt
	global_load_dwordx4 v[230:233], v[136:137], off offset:3072 nt
	v_lshl_add_u64 v[136:137], v[250:251], 0, s[76:77]
	global_load_dwordx4 v[234:237], v[136:137], off nt
	global_load_dwordx4 v[238:241], v[136:137], off offset:1024 nt
	global_load_dwordx4 v[242:245], v[136:137], off offset:2048 nt
	global_load_dwordx4 v[246:249], v[136:137], off offset:3072 nt
	s_waitcnt vmcnt(0)
.LBB0_164:
	v_cmp_lt_i32_e32 vcc, v110, v109
	v_add_u32_e32 v8, s6, v118
	s_mov_b64 s[0:1], s[52:53]
	v_cndmask_b32_e32 v0, v108, v110, vcc
	v_cmp_lt_i32_e32 vcc, v111, v109
	s_mov_b64 s[2:3], s[54:55]
	v_add_u32_e32 v10, 0xfffff000, v8
	v_cndmask_b32_e32 v1, v108, v111, vcc
	v_cmp_lt_i32_e32 vcc, v112, v109
	v_ashrrev_i32_e32 v9, 31, v8
	v_lshlrev_b32_e32 v119, 2, v0
	v_cndmask_b32_e32 v2, v108, v112, vcc
	v_cmp_lt_i32_e32 vcc, v113, v109
	v_mov_b32_e32 v12, s3
	v_mov_b32_e32 v13, s1
	v_cndmask_b32_e32 v3, v108, v113, vcc
	v_cmp_lt_i32_e32 vcc, v114, v109
	v_mov_b32_e32 v14, s2
	v_mov_b32_e32 v15, s0
	v_cndmask_b32_e32 v4, v108, v114, vcc
	v_cmp_lt_i32_e32 vcc, v115, v109
	s_movk_i32 s0, 0x2000
	v_lshlrev_b32_e32 v120, 2, v1
	v_cndmask_b32_e32 v5, v108, v115, vcc
	v_cmp_gt_i32_e32 vcc, s13, v8
	v_lshlrev_b32_e32 v121, 2, v2
	v_lshlrev_b32_e32 v122, 2, v3
	v_cndmask_b32_e32 v11, 0, v9, vcc
	v_cndmask_b32_e32 v10, v10, v8, vcc
	v_lshlrev_b64 v[8:9], 13, v[8:9]
	v_cndmask_b32_e32 v13, v12, v13, vcc
	v_cndmask_b32_e32 v12, v14, v15, vcc
	v_lshlrev_b64 v[10:11], 14, v[10:11]
	v_lshl_add_u64 v[106:107], s[56:57], 0, v[8:9]
	v_lshl_add_u64 v[8:9], v[12:13], 0, v[10:11]
	v_lshl_add_u64 v[24:25], v[8:9], 0, v[72:73]
	v_add_co_u32_e32 v40, vcc, s13, v24
	v_lshlrev_b32_e32 v123, 2, v4
	s_nop 0
	v_addc_co_u32_e32 v41, vcc, 0, v25, vcc
	v_add_co_u32_e32 v42, vcc, s0, v24
	v_lshlrev_b32_e32 v124, 2, v5
	s_nop 0
	v_addc_co_u32_e32 v43, vcc, 0, v25, vcc
	ds_read_b128 v[4:7], v117
	ds_read_b128 v[0:3], v117 offset:16384
	v_add_co_u32_e32 v24, vcc, s12, v24
	s_mov_b32 s0, 0x800000
	s_nop 0
	v_addc_co_u32_e32 v25, vcc, 0, v25, vcc
	s_nop 0
	s_nop 0
	s_nop 0
	v_mov_b32_e32 v20, v186
	v_mov_b32_e32 v21, v187
	v_mov_b32_e32 v22, v188
	v_mov_b32_e32 v23, v189
	v_mov_b32_e32 v16, v190
	v_mov_b32_e32 v17, v191
	v_mov_b32_e32 v18, v192
	v_mov_b32_e32 v19, v193
	v_mov_b32_e32 v12, v194
	v_mov_b32_e32 v13, v195
	v_mov_b32_e32 v14, v196
	v_mov_b32_e32 v15, v197
	v_mov_b32_e32 v8, v198
	v_mov_b32_e32 v9, v199
	v_mov_b32_e32 v10, v200
	v_mov_b32_e32 v11, v201
	v_mov_b32_e32 v36, v202
	v_mov_b32_e32 v37, v203
	v_mov_b32_e32 v38, v204
	v_mov_b32_e32 v39, v205
	v_mov_b32_e32 v32, v206
	v_mov_b32_e32 v33, v207
	v_mov_b32_e32 v34, v208
	v_mov_b32_e32 v35, v209
	v_mov_b32_e32 v28, v210
	v_mov_b32_e32 v29, v211
	v_mov_b32_e32 v30, v212
	v_mov_b32_e32 v31, v213
	v_mov_b32_e32 v24, v214
	v_mov_b32_e32 v25, v215
	v_mov_b32_e32 v26, v216
	v_mov_b32_e32 v27, v217
	v_mov_b32_e32 v68, v218
	v_mov_b32_e32 v69, v219
	v_mov_b32_e32 v70, v220
	v_mov_b32_e32 v71, v221
	v_mov_b32_e32 v64, v222
	v_mov_b32_e32 v65, v223
	v_mov_b32_e32 v66, v224
	v_mov_b32_e32 v67, v225
	v_mov_b32_e32 v60, v226
	v_mov_b32_e32 v61, v227
	v_mov_b32_e32 v62, v228
	v_mov_b32_e32 v63, v229
	v_mov_b32_e32 v56, v230
	v_mov_b32_e32 v57, v231
	v_mov_b32_e32 v58, v232
	v_mov_b32_e32 v59, v233
	v_mov_b32_e32 v52, v234
	v_mov_b32_e32 v53, v235
	v_mov_b32_e32 v54, v236
	v_mov_b32_e32 v55, v237
	v_mov_b32_e32 v48, v238
	v_mov_b32_e32 v49, v239
	v_mov_b32_e32 v50, v240
	v_mov_b32_e32 v51, v241
	v_mov_b32_e32 v44, v242
	v_mov_b32_e32 v45, v243
	v_mov_b32_e32 v46, v244
	v_mov_b32_e32 v47, v245
	v_mov_b32_e32 v40, v246
	v_mov_b32_e32 v41, v247
	v_mov_b32_e32 v42, v248
	v_mov_b32_e32 v43, v249
	v_lshl_add_u64 v[96:97], v[106:107], 0, v[74:75]
	v_lshl_add_u64 v[94:95], v[106:107], 0, v[76:77]
	v_lshl_add_u64 v[92:93], v[106:107], 0, v[78:79]
	s_add_i32 s6, s6, 1
	s_cmp_eq_u32 s6, 4
	s_cbranch_scc1 .Lnorm0_nopf
	v_lshl_add_u64 v[250:251], v[250:251], 0, s[34:35]
	global_load_dwordx4 v[186:189], v[250:251], off nt
	global_load_dwordx4 v[190:193], v[250:251], off offset:1024 nt
	global_load_dwordx4 v[194:197], v[250:251], off offset:2048 nt
	global_load_dwordx4 v[198:201], v[250:251], off offset:3072 nt
	v_lshl_add_u64 v[136:137], v[250:251], 0, s[78:79]
	global_load_dwordx4 v[202:205], v[136:137], off nt
	global_load_dwordx4 v[206:209], v[136:137], off offset:1024 nt
	global_load_dwordx4 v[210:213], v[136:137], off offset:2048 nt
	global_load_dwordx4 v[214:217], v[136:137], off offset:3072 nt
	v_lshl_add_u64 v[136:137], v[250:251], 0, s[32:33]
	global_load_dwordx4 v[218:221], v[136:137], off nt
	global_load_dwordx4 v[222:225], v[136:137], off offset:1024 nt
	global_load_dwordx4 v[226:229], v[136:137], off offset:2048 nt
	global_load_dwordx4 v[230:233], v[136:137], off offset:3072 nt
	v_lshl_add_u64 v[136:137], v[250:251], 0, s[76:77]
	global_load_dwordx4 v[234:237], v[136:137], off nt
	global_load_dwordx4 v[238:241], v[136:137], off offset:1024 nt
	global_load_dwordx4 v[242:245], v[136:137], off offset:2048 nt
	global_load_dwordx4 v[246:249], v[136:137], off offset:3072 nt

.LBB0_1581:
	v_add_u32_e32 v106, s4, v179
	v_ashrrev_i32_e32 v107, 31, v106
	v_lshlrev_b64 v[108:109], 13, v[106:107]
	v_lshl_add_u64 v[132:133], v[66:67], 0, v[108:109]
	global_load_dwordx4 v[0:3], v[68:69], off offset:16
	global_load_dwordx4 v[4:7], v[68:69], off
	global_load_dwordx4 v[8:11], v[68:69], off offset:2064
	global_load_dwordx4 v[12:15], v[68:69], off offset:2048
	global_load_dwordx4 v[16:19], v[70:71], off offset:16
	global_load_dwordx4 v[20:23], v[70:71], off
	global_load_dwordx4 v[24:27], v[72:73], off offset:16
	global_load_dwordx4 v[28:31], v[72:73], off
	global_load_dwordx4 v[32:35], v[74:75], off offset:16
	global_load_dwordx4 v[36:39], v[74:75], off
	global_load_dwordx4 v[40:43], v[76:77], off offset:16
	global_load_dwordx4 v[44:47], v[76:77], off
	global_load_dwordx4 v[48:51], v[78:79], off offset:16
	global_load_dwordx4 v[52:55], v[78:79], off
	global_load_dwordx4 v[56:59], v[80:81], off offset:16
	global_load_dwordx4 v[60:63], v[80:81], off
	global_load_dwordx4 v[136:139], v[132:133], off
	global_load_dwordx4 v[144:147], v[132:133], off offset:1024
	global_load_dwordx4 v[152:155], v[132:133], off offset:2048
	global_load_dwordx4 v[160:163], v[132:133], off offset:3072
	v_add_co_u32_e32 v132, vcc, s2, v132
	v_lshlrev_b64 v[106:107], 14, v[106:107]
	s_nop 0
	v_addc_co_u32_e32 v133, vcc, 0, v133, vcc
	global_load_dwordx4 v[182:185], v[132:133], off
	global_load_dwordx4 v[186:189], v[132:133], off offset:1024
	global_load_dwordx4 v[190:193], v[132:133], off offset:2048
	global_load_dwordx4 v[194:197], v[132:133], off offset:3072
	v_mov_b32_e32 v83, v65
	v_mov_b32_e32 v85, v65
	v_lshl_add_u64 v[130:131], s[54:55], 0, v[106:107]
	v_mov_b32_e32 v87, v65
	v_lshl_add_u64 v[108:109], v[130:131], 0, v[82:83]
	v_lshl_add_u64 v[110:111], v[130:131], 0, v[84:85]
	v_lshl_add_u64 v[112:113], v[130:131], 0, v[86:87]
	s_add_i32 s4, s4, 1
	s_cmp_eq_u32 s4, 4
	v_lshl_add_u64 v[106:107], v[130:131], 0, v[64:65]
	v_lshl_add_u64 v[114:115], v[130:131], 0, v[88:89]
	v_lshl_add_u64 v[116:117], v[130:131], 0, v[90:91]
	v_lshl_add_u64 v[118:119], v[130:131], 0, v[92:93]
	v_lshl_add_u64 v[120:121], v[130:131], 0, v[94:95]
	v_lshl_add_u64 v[122:123], v[130:131], 0, v[96:97]
	v_lshl_add_u64 v[124:125], v[130:131], 0, v[98:99]
	v_lshl_add_u64 v[126:127], v[130:131], 0, v[100:101]
	v_lshl_add_u64 v[128:129], v[130:131], 0, v[102:103]
	v_lshl_add_u64 v[130:131], v[130:131], 0, v[104:105]
	s_waitcnt vmcnt(0)
	v_lshlrev_b32_e32 v132, 16, v136
	v_and_b32_e32 v133, 0xffff0000, v136
	v_lshlrev_b32_e32 v134, 16, v137
	v_and_b32_e32 v135, 0xffff0000, v137
	v_lshlrev_b32_e32 v136, 16, v138
	v_and_b32_e32 v137, 0xffff0000, v138
	v_lshlrev_b32_e32 v138, 16, v139
	v_and_b32_e32 v139, 0xffff0000, v139
	v_lshlrev_b32_e32 v140, 16, v144
	v_and_b32_e32 v141, 0xffff0000, v144
	v_pk_mul_f32 v[198:199], v[132:133], v[132:133]
	v_pk_mul_f32 v[202:203], v[136:137], v[136:137]
	v_lshlrev_b32_e32 v142, 16, v145
	v_and_b32_e32 v143, 0xffff0000, v145
	v_lshlrev_b32_e32 v144, 16, v146
	v_and_b32_e32 v145, 0xffff0000, v146
	v_pk_mul_f32 v[200:201], v[134:135], v[134:135]
	v_pk_mul_f32 v[204:205], v[138:139], v[138:139]
	v_pk_mul_f32 v[206:207], v[140:141], v[140:141]
	v_add_f32_e32 v83, v202, v203
	v_add_f32_e32 v85, v198, v199
	v_lshlrev_b32_e32 v146, 16, v147
	v_and_b32_e32 v147, 0xffff0000, v147
	v_lshlrev_b32_e32 v148, 16, v152
	v_and_b32_e32 v149, 0xffff0000, v152
	v_pk_mul_f32 v[208:209], v[142:143], v[142:143]
	v_pk_mul_f32 v[210:211], v[144:145], v[144:145]
	v_add_f32_e32 v87, v206, v207
	v_add_f32_e32 v83, v83, v204
	v_add_f32_e32 v85, v85, v200
	v_lshlrev_b32_e32 v150, 16, v153
	v_and_b32_e32 v151, 0xffff0000, v153
	v_lshlrev_b32_e32 v152, 16, v154
	v_and_b32_e32 v153, 0xffff0000, v154
	v_pk_mul_f32 v[212:213], v[146:147], v[146:147]
	v_pk_mul_f32 v[214:215], v[148:149], v[148:149]
	v_lshlrev_b32_e32 v234, 16, v186
	v_and_b32_e32 v235, 0xffff0000, v186
	v_add_f32_e32 v181, v210, v211
	v_add_f32_e32 v83, v205, v83
	v_add_f32_e32 v85, v201, v85
	v_add_f32_e32 v87, v87, v208
	v_lshlrev_b32_e32 v154, 16, v155
	v_and_b32_e32 v155, 0xffff0000, v155
	v_lshlrev_b32_e32 v156, 16, v160
	v_and_b32_e32 v157, 0xffff0000, v160
	v_pk_mul_f32 v[216:217], v[150:151], v[150:151]
	v_pk_mul_f32 v[218:219], v[152:153], v[152:153]
	v_add_f32_e32 v246, v214, v215
	v_pk_mul_f32 v[214:215], v[234:235], v[234:235]
	v_add_f32_e32 v87, v209, v87
	v_add_f32_e32 v181, v181, v212
	v_add_f32_e32 v83, v85, v83
	v_lshlrev_b32_e32 v158, 16, v161
	v_and_b32_e32 v159, 0xffff0000, v161
	v_lshlrev_b32_e32 v160, 16, v162
	v_and_b32_e32 v161, 0xffff0000, v162
	v_pk_mul_f32 v[220:221], v[154:155], v[154:155]
	v_pk_mul_f32 v[222:223], v[156:157], v[156:157]
	v_add_f32_e32 v247, v218, v219
	v_add_f32_e32 v252, v214, v215
	v_add_f32_e32 v181, v213, v181
	v_add_f32_e32 v214, v246, v216
	v_add_f32_e32 v83, v83, v87
	v_lshlrev_b32_e32 v162, 16, v163
	v_and_b32_e32 v163, 0xffff0000, v163
	v_pk_mul_f32 v[224:225], v[158:159], v[158:159]
	v_pk_mul_f32 v[226:227], v[160:161], v[160:161]
	v_lshlrev_b32_e32 v230, 16, v182
	v_and_b32_e32 v231, 0xffff0000, v182
	v_lshlrev_b32_e32 v232, 16, v184
	v_and_b32_e32 v233, 0xffff0000, v184
	v_add_f32_e32 v248, v222, v223
	v_add_f32_e32 v246, v217, v214
	v_add_f32_e32 v216, v247, v220
	v_add_f32_e32 v83, v83, v181
	v_pk_mul_f32 v[228:229], v[162:163], v[162:163]
	v_lshlrev_b32_e32 v182, 16, v183
	v_and_b32_e32 v183, 0xffff0000, v183
	v_lshlrev_b32_e32 v236, 16, v188
	v_and_b32_e32 v237, 0xffff0000, v188
	v_and_b32_e32 v239, 0xffff0000, v190
	v_and_b32_e32 v241, 0xffff0000, v192
	v_and_b32_e32 v243, 0xffff0000, v194
	v_and_b32_e32 v245, 0xffff0000, v196
	v_add_f32_e32 v249, v226, v227
	v_pk_mul_f32 v[198:199], v[230:231], v[230:231]
	v_pk_mul_f32 v[206:207], v[232:233], v[232:233]
	v_add_f32_e32 v220, v221, v216
	v_add_f32_e32 v221, v248, v224
	v_add_f32_e32 v83, v83, v246
	v_lshlrev_b32_e32 v184, 16, v185
	v_and_b32_e32 v185, 0xffff0000, v185
	v_lshlrev_b32_e32 v238, 16, v190
	v_lshlrev_b32_e32 v240, 16, v192
	v_lshlrev_b32_e32 v242, 16, v194
	v_lshlrev_b32_e32 v244, 16, v196
	v_pk_mul_f32 v[202:203], v[182:183], v[182:183]
	v_pk_mul_f32 v[222:223], v[236:237], v[236:237]
	v_add_f32_e32 v250, v198, v199
	v_add_f32_e32 v251, v206, v207
	v_mov_b32_e32 v206, v239
	v_mov_b32_e32 v207, v241
	v_mov_b32_e32 v212, v243
	v_mov_b32_e32 v213, v245
	v_add_f32_e32 v224, v249, v228
	v_add_f32_e32 v221, v225, v221
	v_add_f32_e32 v83, v83, v220
	v_lshlrev_b32_e32 v186, 16, v187
	v_and_b32_e32 v187, 0xffff0000, v187
	v_pk_mul_f32 v[210:211], v[184:185], v[184:185]
	v_mov_b32_e32 v198, v238
	v_mov_b32_e32 v199, v240
	v_mov_b32_e32 v208, v242
	v_mov_b32_e32 v209, v244
	v_add_f32_e32 v222, v222, v223
	v_pk_mul_f32 v[206:207], v[206:207], v[206:207]
	v_pk_mul_f32 v[212:213], v[212:213], v[212:213]
	v_add_f32_e32 v223, v229, v224
	v_add_f32_e32 v202, v250, v202
	v_add_f32_e32 v83, v83, v221
	v_lshlrev_b32_e32 v188, 16, v189
	v_and_b32_e32 v189, 0xffff0000, v189
	v_pk_mul_f32 v[218:219], v[186:187], v[186:187]
	v_pk_fma_f32 v[198:199], v[198:199], v[198:199], v[206:207]
	v_pk_fma_f32 v[206:207], v[208:209], v[208:209], v[212:213]
	v_add_f32_e32 v208, v251, v210
	v_add_f32_e32 v85, v203, v202
	v_add_f32_e32 v83, v83, v223
	v_lshlrev_b32_e32 v190, 16, v191
	v_lshlrev_b32_e32 v192, 16, v193
	v_lshlrev_b32_e32 v194, 16, v195
	v_lshlrev_b32_e32 v196, 16, v197
	v_pk_mul_f32 v[226:227], v[188:189], v[188:189]
	v_add_f32_e32 v209, v252, v218
	v_add_f32_e32 v202, v211, v208
	v_add_f32_e32 v83, v83, v85
	v_and_b32_e32 v191, 0xffff0000, v191
	v_and_b32_e32 v193, 0xffff0000, v193
	v_mov_b32_e32 v204, v190
	v_mov_b32_e32 v205, v192
	v_mov_b32_e32 v214, v194
	v_mov_b32_e32 v215, v196
	v_add_f32_e32 v210, v222, v226
	v_add_f32_e32 v203, v219, v209
	v_add_f32_e32 v83, v83, v202
	v_mov_b32_e32 v200, v191
	v_mov_b32_e32 v201, v193
	v_pk_fma_f32 v[198:199], v[204:205], v[204:205], v[198:199]
	v_pk_fma_f32 v[204:205], v[214:215], v[214:215], v[206:207]
	v_add_f32_e32 v206, v227, v210
	v_add_f32_e32 v83, v83, v203
	v_and_b32_e32 v195, 0xffff0000, v195
	v_and_b32_e32 v197, 0xffff0000, v197
	v_pk_fma_f32 v[198:199], v[200:201], v[200:201], v[198:199]
	v_add_f32_e32 v83, v83, v206
	v_mov_b32_e32 v216, v195
	v_mov_b32_e32 v217, v197
	v_add_f32_e32 v83, v83, v198
	v_pk_fma_f32 v[200:201], v[216:217], v[216:217], v[204:205]
	v_add_f32_e32 v83, v83, v199
	v_add_f32_e32 v83, v83, v200
	v_add_f32_e32 v83, v83, v201
	ds_bpermute_b32 v85, v173, v83
	s_waitcnt lgkmcnt(0)
	v_add_f32_e32 v83, v83, v85
	ds_bpermute_b32 v85, v174, v83
	s_waitcnt lgkmcnt(0)
	v_add_f32_e32 v83, v83, v85
	ds_bpermute_b32 v85, v175, v83
	s_waitcnt lgkmcnt(0)
	v_add_f32_e32 v83, v83, v85
	ds_bpermute_b32 v85, v176, v83
	s_waitcnt lgkmcnt(0)
	v_add_f32_e32 v83, v83, v85
	ds_bpermute_b32 v85, v177, v83
	s_waitcnt lgkmcnt(0)
	v_add_f32_e32 v83, v83, v85
	ds_bpermute_b32 v85, v178, v83
	s_waitcnt lgkmcnt(0)
	v_add_f32_e32 v83, v83, v85
	v_fmamk_f32 v83, v83, 0x39800000, v164
	v_mul_f32_e32 v85, 0x4b800000, v83
	v_cmp_gt_f32_e32 vcc, s3, v83
	s_nop 1
	v_cndmask_b32_e32 v83, v83, v85, vcc
	v_rsq_f32_e32 v83, v83
	s_nop 0
	v_mul_f32_e32 v85, 0x45800000, v83
	v_cndmask_b32_e32 v198, v83, v85, vcc
	v_pk_mul_f32 v[132:133], v[198:199], v[132:133] op_sel_hi:[0,1]
	v_pk_mul_f32 v[134:135], v[198:199], v[134:135] op_sel_hi:[0,1]
	v_pk_mul_f32 v[136:137], v[198:199], v[136:137] op_sel_hi:[0,1]
	v_pk_mul_f32 v[138:139], v[198:199], v[138:139] op_sel_hi:[0,1]
	v_pk_mul_f32 v[140:141], v[198:199], v[140:141] op_sel_hi:[0,1]
	v_pk_mul_f32 v[142:143], v[198:199], v[142:143] op_sel_hi:[0,1]
	v_pk_mul_f32 v[144:145], v[198:199], v[144:145] op_sel_hi:[0,1]
	v_pk_mul_f32 v[146:147], v[198:199], v[146:147] op_sel_hi:[0,1]
	v_pk_mul_f32 v[148:149], v[198:199], v[148:149] op_sel_hi:[0,1]
	v_pk_mul_f32 v[150:151], v[198:199], v[150:151] op_sel_hi:[0,1]
	v_pk_mul_f32 v[152:153], v[198:199], v[152:153] op_sel_hi:[0,1]
	v_pk_mul_f32 v[154:155], v[198:199], v[154:155] op_sel_hi:[0,1]
	v_pk_mul_f32 v[156:157], v[198:199], v[156:157] op_sel_hi:[0,1]
	v_pk_mul_f32 v[158:159], v[198:199], v[158:159] op_sel_hi:[0,1]
	v_pk_mul_f32 v[160:161], v[198:199], v[160:161] op_sel_hi:[0,1]
	v_pk_mul_f32 v[162:163], v[198:199], v[162:163] op_sel_hi:[0,1]
	v_pk_mul_f32 v[200:201], v[198:199], v[230:231] op_sel_hi:[0,1]
	v_pk_mul_f32 v[182:183], v[198:199], v[182:183] op_sel_hi:[0,1]
	v_pk_mul_f32 v[202:203], v[198:199], v[232:233] op_sel_hi:[0,1]
	v_pk_mul_f32 v[184:185], v[198:199], v[184:185] op_sel_hi:[0,1]
	v_pk_mul_f32 v[204:205], v[198:199], v[234:235] op_sel_hi:[0,1]
	v_pk_mul_f32 v[186:187], v[198:199], v[186:187] op_sel_hi:[0,1]
	v_pk_mul_f32 v[206:207], v[198:199], v[236:237] op_sel_hi:[0,1]
	v_pk_mul_f32 v[188:189], v[198:199], v[188:189] op_sel_hi:[0,1]
	v_pk_mul_f32 v[208:209], v[198:199], v[238:239] op_sel_hi:[0,1]
	v_pk_mul_f32 v[190:191], v[198:199], v[190:191] op_sel_hi:[0,1]
	v_pk_mul_f32 v[210:211], v[198:199], v[240:241] op_sel_hi:[0,1]
	v_pk_mul_f32 v[192:193], v[198:199], v[192:193] op_sel_hi:[0,1]
	v_pk_mul_f32 v[212:213], v[198:199], v[242:243] op_sel_hi:[0,1]
	v_pk_mul_f32 v[194:195], v[198:199], v[194:195] op_sel_hi:[0,1]
	v_pk_mul_f32 v[214:215], v[198:199], v[244:245] op_sel_hi:[0,1]
	v_pk_mul_f32 v[196:197], v[198:199], v[196:197] op_sel_hi:[0,1]
	v_pk_mul_f32 v[4:5], v[4:5], v[132:133]
	v_pk_mul_f32 v[6:7], v[6:7], v[134:135]
	v_pk_mul_f32 v[0:1], v[0:1], v[136:137]
	v_pk_mul_f32 v[2:3], v[2:3], v[138:139]
	v_pk_mul_f32 v[12:13], v[12:13], v[140:141]
	v_pk_mul_f32 v[14:15], v[14:15], v[142:143]
	v_pk_mul_f32 v[8:9], v[144:145], v[8:9]
	v_pk_mul_f32 v[10:11], v[146:147], v[10:11]
	v_pk_mul_f32 v[20:21], v[148:149], v[20:21]
	v_pk_mul_f32 v[22:23], v[150:151], v[22:23]
	v_pk_mul_f32 v[16:17], v[152:153], v[16:17]
	v_pk_mul_f32 v[18:19], v[154:155], v[18:19]
	v_pk_mul_f32 v[28:29], v[156:157], v[28:29]
	v_pk_mul_f32 v[30:31], v[158:159], v[30:31]
	v_pk_mul_f32 v[24:25], v[160:161], v[24:25]
	v_pk_mul_f32 v[26:27], v[162:163], v[26:27]
	v_pk_mul_f32 v[36:37], v[200:201], v[36:37]
	v_pk_mul_f32 v[38:39], v[182:183], v[38:39]
	v_pk_mul_f32 v[32:33], v[202:203], v[32:33]
	v_pk_mul_f32 v[34:35], v[184:185], v[34:35]
	v_pk_mul_f32 v[44:45], v[204:205], v[44:45]
	v_pk_mul_f32 v[46:47], v[186:187], v[46:47]
	v_pk_mul_f32 v[40:41], v[206:207], v[40:41]
	v_pk_mul_f32 v[42:43], v[188:189], v[42:43]
	v_pk_mul_f32 v[52:53], v[208:209], v[52:53]
	v_pk_mul_f32 v[54:55], v[190:191], v[54:55]
	v_pk_mul_f32 v[48:49], v[210:211], v[48:49]
	v_pk_mul_f32 v[50:51], v[192:193], v[50:51]
	v_pk_mul_f32 v[60:61], v[212:213], v[60:61]
	v_pk_mul_f32 v[62:63], v[194:195], v[62:63]
	v_pk_mul_f32 v[56:57], v[214:215], v[56:57]
	v_pk_mul_f32 v[58:59], v[196:197], v[58:59]
	global_store_dwordx4 v[106:107], v[4:7], off nt
	global_store_dwordx4 v[106:107], v[0:3], off offset:16 nt
	global_store_dwordx4 v[106:107], v[12:15], off offset:2048 nt
	global_store_dwordx4 v[106:107], v[8:11], off offset:2064 nt
	global_store_dwordx4 v[108:109], v[20:23], off nt
	global_store_dwordx4 v[110:111], v[16:19], off nt
	global_store_dwordx4 v[112:113], v[28:31], off nt
	global_store_dwordx4 v[114:115], v[24:27], off nt
	global_store_dwordx4 v[116:117], v[36:39], off nt
	global_store_dwordx4 v[118:119], v[32:35], off nt
	global_store_dwordx4 v[120:121], v[44:47], off nt
	global_store_dwordx4 v[122:123], v[40:43], off nt
	global_store_dwordx4 v[124:125], v[52:55], off nt
	global_store_dwordx4 v[126:127], v[48:51], off nt
	global_store_dwordx4 v[128:129], v[60:63], off nt
	global_store_dwordx4 v[130:131], v[56:59], off nt
	s_cbranch_scc0 .LBB0_1581
	s_add_i32 s96, s96, s94
	s_add_i32 s0, s0, s1
	s_cmpk_gt_i32 s96, 0xff
	s_cbranch_scc0 .LBB0_1580
